# prep unit step 1: scalar loads into dedicated registers (no wait before the main loads), wave 6 issues its three scalar loads together, 18th tile load hoisted above the wait
# baseline (speedup 1.0000x reference)
; __device__ __forceinline__ float softplus_f(float x) { return fmaxf(x, 0.f) + log1pf(__expf(-fabsf(x))); }
; __device__ void prep_unit(unsigned char* lds, int bh, int n, const bf16_t* pc, const float* scal, const float* convw  , float alog, float dtb, unsigned char* unit, float* egl, unsigned* flag, unsigned fval) {
;     ...
;     } else if (tid < 448) {
;         const int t = tid - 384; const float* sp = scal + (row0 + t) * 16;
;         bet[t] = 1.0f / (1.0f + __expf(-sp[4 + h]));
;         gc[t] = -__expf(alog) * softplus_f(sp[8 + h] + dtb);
;     }
; __device__ void run_phase(const Params& p, unsigned char* lds, int ph) {
;     ...
;                 prep_unit(lds, bh, n, (const bf16_t*)(ws + WS_PC), (const float*)(ws + WS_SCAL), p.in[I_CONVW] + (size_t)l * 4 * 1536, p.in[I_ALOG][l * 4 + h], p.in[I_DTB][l * 4 + h],
;                           ws + WS_PREP + (size_t)(bh * 128 + n) * PREP_UNIT, (float*)(ws + WS_EGL), uflag + bh * 128 + n, fval); }
.LBB0_302:
	s_or_saveexec_b64 s[12:13], s[0:1]
	v_readlane_b32 s4, v255, 45
	v_readlane_b32 s5, v255, 46
	s_xor_b64 exec, exec, s[12:13]
	s_cbranch_execz .LBB0_449
	v_and_b32_e32 v2, 3, v90
	v_or_b32_e32 v4, s48, v2
	v_ashrrev_i32_e32 v5, 31, v4
	v_readlane_b32 s0, v254, 61
	v_lshlrev_b64 v[4:5], 2, v[4:5]
	v_readlane_b32 s1, v254, 62
	v_subrev_u32_e32 v0, 48, v90
	v_lshrrev_b32_e32 v0, 4, v0
	v_lshl_add_u64 v[6:7], s[0:1], 0, v[4:5]
	v_readlane_b32 s0, v254, 63
	v_readlane_b32 s1, v255, 0
	global_load_dword v252, v[6:7], off
	v_mov_b32_e32 v156, v212
	v_lshl_add_u64 v[4:5], s[0:1], 0, v[4:5]
	global_load_dword v253, v[4:5], off
	v_lshlrev_b32_e32 v5, 11, v90
	s_movk_i32 s0, 0x17f
	v_and_b32_e32 v6, 0x6000, v5
	v_and_b32_e32 v157, 63, v156
	v_mov_b32_e32 v7, v1
	v_lshlrev_b64 v[8:9], 6, v[0:1]
	v_cmp_lt_i32_e32 vcc, s0, v156
	s_movk_i32 s0, 0x7f
	v_lshl_add_u64 v[22:23], v[8:9], 0, v[6:7]
	v_cmp_gt_u32_e64 s[10:11], s46, v156
	v_cmp_lt_u32_e64 s[8:9], s0, v156
	v_cmp_gt_u32_e64 s[6:7], 8, v157
	s_and_saveexec_b64 s[0:1], vcc
	s_xor_b64 s[0:1], exec, s[0:1]
	s_cbranch_execz .LBB0_307
	s_movk_i32 s2, 0x1c0
	v_cmp_gt_u32_e32 vcc, s2, v156
	s_and_saveexec_b64 s[2:3], vcc
	s_cbranch_execz .LBB0_306
	v_add_u32_e32 v6, 0xfffffe80, v156
	v_mov_b32_e32 v7, v1
	v_lshl_add_u64 v[8:9], v[22:23], 0, v[6:7]
	v_readlane_b32 s4, v255, 37
	v_lshlrev_b64 v[8:9], 6, v[8:9]
	v_readlane_b32 s5, v255, 38
	v_lshlrev_b32_e32 v10, 2, v2
	v_mov_b32_e32 v11, v1
	v_lshl_add_u64 v[8:9], s[4:5], 0, v[8:9]
	v_lshl_add_u64 v[8:9], v[8:9], 0, v[10:11]
	v_lshl_add_u32 v5, v6, 2, 0
	v_add_u32_e32 v6, 0x22100, v5
	s_branch .Lps1_a
.Lps1_back:
	v_mul_f32_e32 v2, 0x3fb8aa3b, v252
	v_add_u32_e32 v3, 0x22000, v5
	v_mov_b32_e32 v5, v224
	s_nop 0
	v_exp_f32_e32 v2, v2
	s_waitcnt vmcnt(0) lgkmcnt(0)
	v_mul_f32_e32 v5, 0xbfb8aa3b, v5
	v_exp_f32_e32 v5, v5
	s_nop 0
	v_add_f32_e32 v5, 1.0, v5
	v_div_scale_f32 v7, s[4:5], v5, v5, 1.0
	v_rcp_f32_e32 v10, v7
	s_mov_b32 s4, 0xbfb8aa3b
	v_fma_f32 v11, -v7, v10, 1.0
	v_fmac_f32_e32 v10, v11, v10
	v_div_scale_f32 v11, vcc, 1.0, v5, 1.0
	v_mul_f32_e32 v12, v11, v10
	v_fma_f32 v13, -v7, v12, v11
	v_fmac_f32_e32 v12, v13, v10
	v_fma_f32 v7, -v7, v12, v11
	v_div_fmas_f32 v7, v7, v10, v12
	v_div_fixup_f32 v5, v7, v5, 1.0
	ds_write_b32 v6, v5
	v_mov_b32_e32 v5, v225
	s_nop 0
	s_waitcnt vmcnt(0) lgkmcnt(0)
	v_add_f32_e32 v5, v253, v5
	v_max_f32_e32 v4, 0, v5
	v_mul_f32_e64 v5, |v5|, s4
	v_exp_f32_e32 v5, v5
	s_mov_b32 s4, 0x3f2aaaab
	v_add_f32_e32 v8, 1.0, v5
	v_add_f32_e32 v6, -1.0, v8
	v_sub_f32_e32 v7, v6, v8
	v_add_f32_e32 v7, 1.0, v7
	v_sub_f32_e32 v6, v5, v6
	v_add_f32_e32 v9, v6, v7
	v_frexp_mant_f32_e32 v6, v8
	v_cmp_gt_f32_e32 vcc, s4, v6
	v_cvt_f64_f32_e32 v[6:7], v8
	v_frexp_exp_i32_f64_e32 v6, v[6:7]
	v_subbrev_co_u32_e32 v6, vcc, 0, v6, vcc
	v_sub_u32_e32 v7, 0, v6
	v_ldexp_f32 v8, v8, v7
	v_ldexp_f32 v7, v9, v7
	v_add_f32_e32 v9, -1.0, v8
	v_add_f32_e32 v10, 1.0, v9
	v_sub_f32_e32 v10, v8, v10
	v_add_f32_e32 v10, v7, v10
	v_add_f32_e32 v11, v9, v10
	v_sub_f32_e32 v9, v11, v9
	v_sub_f32_e32 v9, v10, v9
	v_add_f32_e32 v10, 1.0, v8
	v_add_f32_e32 v12, -1.0, v10
	v_sub_f32_e32 v8, v8, v12
	v_add_f32_e32 v7, v7, v8
	v_add_f32_e32 v8, v10, v7
	v_sub_f32_e32 v10, v8, v10
	v_sub_f32_e32 v7, v7, v10
	v_rcp_f32_e32 v10, v8
	v_cvt_f32_i32_e32 v6, v6
	s_mov_b32 s4, 0x3f317218
	v_mul_f32_e32 v12, v11, v10
	v_mul_f32_e32 v13, v8, v12
	v_fma_f32 v14, v12, v8, -v13
	v_fmac_f32_e32 v14, v12, v7
	v_add_f32_e32 v15, v13, v14
	v_sub_f32_e32 v16, v11, v15
	v_sub_f32_e32 v11, v11, v16
	v_sub_f32_e32 v13, v15, v13
	v_sub_f32_e32 v11, v11, v15
	v_add_f32_e32 v9, v9, v11
	v_sub_f32_e32 v11, v13, v14
	v_add_f32_e32 v9, v11, v9
	v_add_f32_e32 v11, v16, v9
	v_mul_f32_e32 v13, v10, v11
	v_mul_f32_e32 v14, v8, v13
	v_fma_f32 v8, v13, v8, -v14
	v_fmac_f32_e32 v8, v13, v7
	v_sub_f32_e32 v7, v16, v11
	v_add_f32_e32 v7, v9, v7
	v_add_f32_e32 v9, v14, v8
	v_sub_f32_e32 v15, v11, v9
	v_sub_f32_e32 v11, v11, v15
	v_sub_f32_e32 v14, v9, v14
	v_sub_f32_e32 v9, v11, v9
	v_add_f32_e32 v7, v7, v9
	v_sub_f32_e32 v8, v14, v8
	v_add_f32_e32 v7, v8, v7
	v_add_f32_e32 v8, v12, v13
	v_add_f32_e32 v7, v15, v7
	v_sub_f32_e32 v9, v8, v12
	v_mul_f32_e32 v7, v10, v7
	v_sub_f32_e32 v9, v13, v9
	v_add_f32_e32 v7, v9, v7
	v_mul_f32_e32 v12, 0x3f317218, v6
	v_add_f32_e32 v9, v8, v7
	v_fma_f32 v13, v6, s4, -v12
	v_mul_f32_e32 v10, v9, v9
	v_fmac_f32_e32 v13, 0xb102e308, v6
	v_sub_f32_e32 v6, v9, v8
	v_fmamk_f32 v11, v10, 0x3e9b6dac, v216
	v_sub_f32_e32 v6, v7, v6
	v_add_f32_e32 v7, v12, v13
	v_fmaak_f32 v11, v10, v11, 0x3f2aaada
	v_sub_f32_e32 v8, v7, v12
	v_ldexp_f32 v12, v9, 1
	v_mul_f32_e32 v9, v9, v10
	v_mul_f32_e32 v9, v9, v11
	v_add_f32_e32 v10, v12, v9
	v_sub_f32_e32 v11, v10, v12
	v_ldexp_f32 v6, v6, 1
	v_sub_f32_e32 v9, v9, v11
	v_add_f32_e32 v6, v6, v9
	v_add_f32_e32 v9, v10, v6
	v_sub_f32_e32 v10, v9, v10
	v_sub_f32_e32 v6, v6, v10
	v_add_f32_e32 v10, v7, v9
	v_sub_f32_e32 v11, v10, v7
	v_sub_f32_e32 v12, v10, v11
	v_sub_f32_e32 v8, v13, v8
	v_sub_f32_e32 v7, v7, v12
	v_sub_f32_e32 v9, v9, v11
	v_add_f32_e32 v7, v9, v7
	v_add_f32_e32 v9, v8, v6
	v_sub_f32_e32 v11, v9, v8
	v_sub_f32_e32 v12, v9, v11
	v_sub_f32_e32 v8, v8, v12
	v_sub_f32_e32 v6, v6, v11
	v_add_f32_e32 v7, v9, v7
	v_add_f32_e32 v6, v6, v8
	v_add_f32_e32 v8, v10, v7
	v_sub_f32_e32 v9, v8, v10
	v_sub_f32_e32 v7, v7, v9
	v_add_f32_e32 v6, v6, v7
	s_mov_b32 s4, 0x7f800000
	v_add_f32_e32 v6, v8, v6
	v_cmp_neq_f32_e32 vcc, s4, v5
	s_mov_b32 s4, 0x33800000
	s_nop 0
	v_cndmask_b32_e32 v6, v220, v6, vcc
	v_cmp_ngt_f32_e32 vcc, -1.0, v5
	s_nop 1
	v_cndmask_b32_e32 v6, v221, v6, vcc
	v_cmp_neq_f32_e32 vcc, -1.0, v5
	s_nop 1
	v_cndmask_b32_e32 v6, v222, v6, vcc
	v_cmp_lt_f32_e64 vcc, |v5|, s4
	s_nop 1
	v_cndmask_b32_e32 v5, v6, v5, vcc
	v_add_f32_e32 v4, v4, v5
	v_mul_f32_e64 v2, v4, -v2
	ds_write_b32 v3, v2

; __device__ void prep_unit(unsigned char* lds, int bh, int n, const bf16_t* pc, const float* scal, const float* convw  , float alog, float dtb, unsigned char* unit, float* egl, unsigned* flag, unsigned fval) {
;     ...
;     if (tid < 384) {
;         const int part = tid >> 7, cg8 = (tid & 127) >> 3, run = tid & 7, col = part * 512 + h * 128 + cg8 * 8;
;         float w[4][8];
; #pragma unroll
;         for (int i = 0; i < 4; ++i) { const f32x4 w0 = *(const f32x4*)(convw + i * 1536 + col), w1 = *(const f32x4*)(convw + i * 1536 + col + 4);
; #pragma unroll
;             for (int j = 0; j < 4; ++j) { w[i][j] = w0[j]; w[i][4 + j] = w1[j]; } }
;         u32x4 xr[11];
; #pragma unroll
;         for (int i = 0; i < 11; ++i) { const int tl = run * 8 - 3 + i; const bool ok = (n > 0) || (tl >= 0);
;             xr[i] = ok ? __builtin_nontemporal_load((const u32x4*)(pc + (row0 + tl) * 1536 + col)) : (u32x4){0u, 0u, 0u, 0u}; }
.LBB0_307:
	s_or_saveexec_b64 s[0:1], s[0:1]
	v_and_b32_e32 v91, 7, v156
	s_xor_b64 exec, exec, s[0:1]
	s_cbranch_execz .LBB0_318
	v_ashrrev_i32_e32 v18, 7, v156
	s_nop 0
	v_and_b32_e32 v42, 0x78, v156
	s_waitcnt lgkmcnt(0)
	v_lshlrev_b32_e32 v3, 9, v18
	v_lshlrev_b32_e32 v2, 7, v2
	v_or3_b32 v20, v3, v2, v42
	v_readlane_b32 s2, v255, 41
	v_ashrrev_i32_e32 v21, 31, v20
	v_readlane_b32 s3, v255, 42
	v_lshlrev_b32_e32 v19, 3, v91
	v_mov_b32_e32 v82, 0
	v_lshl_add_u64 v[10:11], v[20:21], 2, s[2:3]
	v_add_co_u32_e32 v2, vcc, 0x1000, v10
	global_load_dwordx4 v[66:69], v[10:11], off
	global_load_dwordx4 v[14:17], v[10:11], off offset:16
	v_addc_co_u32_e32 v3, vcc, 0, v11, vcc
	v_add_co_u32_e32 v6, vcc, 0x3000, v10
	global_load_dwordx4 v[70:73], v[2:3], off offset:2048
	s_nop 0
	global_load_dwordx4 v[2:5], v[2:3], off offset:2064
	v_addc_co_u32_e32 v7, vcc, 0, v11, vcc
	v_add_co_u32_e32 v10, vcc, 0x4000, v10
	global_load_dwordx4 v[74:77], v[6:7], off
	s_nop 0
	global_load_dwordx4 v[6:9], v[6:7], off offset:16
	v_addc_co_u32_e32 v11, vcc, 0, v11, vcc
	global_load_dwordx4 v[78:81], v[10:11], off offset:2048
	s_nop 0
	global_load_dwordx4 v[10:13], v[10:11], off offset:2064
	v_readlane_b32 s2, v255, 35
	v_readlane_b32 s3, v255, 36
	v_mov_b32_e32 v86, 0
	v_mov_b32_e32 v87, 0
	v_lshl_add_u64 v[24:25], v[20:21], 1, s[2:3]
	v_or_b32_e32 v20, v91, v0
	v_cmp_ne_u32_e32 vcc, 0, v20
	v_mov_b32_e32 v88, 0
	v_mov_b32_e32 v89, 0
	s_and_saveexec_b64 s[2:3], vcc
	s_cbranch_execz .LBB0_310
	v_add_u32_e32 v20, -3, v19
	v_ashrrev_i32_e32 v21, 31, v20
	v_lshl_add_u64 v[20:21], v[22:23], 0, v[20:21]
	v_mad_u64_u32 v[26:27], s[4:5], v20, s53, v[24:25]
	v_mad_i32_i24 v27, v21, s53, v27
	global_load_dwordx4 v[86:89], v[26:27], off nt

; __device__ void prep_unit(unsigned char* lds, int bh, int n, const bf16_t* pc, const float* scal, const float* convw  , float alog, float dtb, unsigned char* unit, float* egl, unsigned* flag, unsigned fval) {
;     ...
;         for (int i = 0; i < 11; ++i) { const int tl = run * 8 - 3 + i; const bool ok = (n > 0) || (tl >= 0);
;             xr[i] = ok ? __builtin_nontemporal_load((const u32x4*)(pc + (row0 + tl) * 1536 + col)) : (u32x4){0u, 0u, 0u, 0u}; }
;         float y[8][8];
; #pragma unroll
;         for (int t = 0; t < 8; ++t)
; #pragma unroll
;             for (int j = 0; j < 8; ++j) y[t][j] = 0.f;
; #pragma unroll
;         for (int i = 0; i < 11; ++i) { float xf[8]; unpack8(xr[i], xf);
; #pragma unroll
;             for (int t = 0; t < 8; ++t) { const int wi = i - t; if (wi >= 0 && wi < 4) {
; #pragma unroll
;                 for (int j = 0; j < 8; ++j) y[t][j] += w[wi][j] * xf[j]; } } }
.LBB0_314:
	s_or_b64 exec, exec, s[2:3]
	v_cmp_eq_u32_e32 vcc, 1, v18
	v_mov_b32_e32 v20, 0x11000
	v_mov_b32_e32 v21, 0x8800
	v_or_b32_e32 v22, v19, v22
	v_cndmask_b32_e32 v20, v20, v21, vcc
	v_cmp_gt_i32_e32 vcc, 2, v18
	v_mad_u64_u32 v[18:19], s[2:3], v22, s53, v[24:25]
	v_mad_u32_u24 v19, v23, s53, v19
	global_load_dwordx4 v[58:61], v[18:19], off nt
	v_or_b32_e32 v18, 1, v22
	v_mad_u64_u32 v[18:19], s[2:3], v18, s53, v[24:25]
	v_mad_u32_u24 v19, v23, s53, v19
	global_load_dwordx4 v[62:65], v[18:19], off nt
	v_or_b32_e32 v18, 2, v22
	v_mad_u64_u32 v[18:19], s[2:3], v18, s53, v[24:25]
	v_mad_u32_u24 v19, v23, s53, v19
	global_load_dwordx4 v[44:47], v[18:19], off nt
	v_or_b32_e32 v18, 3, v22
	v_mad_u64_u32 v[18:19], s[2:3], v18, s53, v[24:25]
	v_mad_u32_u24 v19, v23, s53, v19
	global_load_dwordx4 v[48:51], v[18:19], off nt
	v_or_b32_e32 v18, 4, v22
	v_mad_u64_u32 v[18:19], s[2:3], v18, s53, v[24:25]
	v_mad_u32_u24 v19, v23, s53, v19
	global_load_dwordx4 v[34:37], v[18:19], off nt
	v_or_b32_e32 v18, 5, v22
	v_mad_u64_u32 v[18:19], s[2:3], v18, s53, v[24:25]
	v_mad_u32_u24 v19, v23, s53, v19
	global_load_dwordx4 v[38:41], v[18:19], off nt
	v_or_b32_e32 v18, 6, v22
	v_or_b32_e32 v22, 7, v22
	v_mad_u64_u32 v[18:19], s[2:3], v18, s53, v[24:25]
	v_mad_u64_u32 v[24:25], s[2:3], v22, s53, v[24:25]
	v_add_u32_e32 v20, 0, v20
	v_mad_u32_u24 v19, v23, s53, v19
	v_mad_u32_u24 v25, v23, s53, v25
	v_cndmask_b32_e64 v43, v20, 0, s[10:11]
	global_load_dwordx4 v[18:21], v[18:19], off nt
	global_load_dwordx4 v[22:25], v[24:25], off nt
	s_waitcnt vmcnt(0) lgkmcnt(0)
	v_and_b32_e32 v130, 0xffff0000, v84
	v_and_b32_e32 v26, 0xffff0000, v88
	v_mov_b32_e32 v27, v130
	v_pk_fma_f32 v[136:137], v[14:15], v[26:27], 0 op_sel:[1,0,0] op_sel_hi:[1,1,0]
	v_lshlrev_b32_e32 v138, 16, v56
	v_lshlrev_b32_e32 v27, 16, v84
	v_lshlrev_b32_e32 v26, 16, v88
	v_pk_fma_f32 v[28:29], v[14:15], v[26:27], 0 op_sel_hi:[0,1,0]
	v_and_b32_e32 v128, 0xffff0000, v85
	v_lshlrev_b32_e32 v133, 16, v85
	v_lshlrev_b32_e32 v84, 16, v87
	v_lshlrev_b32_e32 v85, 16, v83
	v_and_b32_e32 v126, 0xffff0000, v89
	v_lshlrev_b32_e32 v132, 16, v89
	v_pk_fma_f32 v[88:89], v[68:69], v[84:85], 0 op_sel_hi:[0,1,0]
	v_and_b32_e32 v131, 0xffff0000, v56
	v_mov_b32_e32 v56, v77
	v_lshlrev_b32_e32 v158, 5, v91
	v_lshlrev_b32_e32 v104, 16, v57
	v_mov_b32_e32 v127, v128
	v_lshlrev_b32_e32 v139, 16, v60
	v_pk_mov_b32 v[26:27], v[26:27], v[138:139] op_sel:[1,0]
	v_mov_b32_e32 v134, v139
	v_pk_fma_f32 v[144:145], v[2:3], v[26:27], v[28:29] op_sel_hi:[0,1,1]
	v_pk_fma_f32 v[26:27], v[14:15], v[138:139], 0 op_sel_hi:[0,1,0]
	v_lshlrev_b32_e32 v135, 16, v64
	v_pk_fma_f32 v[120:121], v[2:3], v[134:135], v[26:27] op_sel_hi:[0,1,1]
	v_lshlrev_b32_e32 v26, 16, v55
	v_lshlrev_b32_e32 v27, 16, v59
	v_pk_mov_b32 v[84:85], v[84:85], v[26:27] op_sel:[1,0]
	v_lshlrev_b32_e32 v29, 16, v63
	v_pk_fma_f32 v[84:85], v[72:73], v[84:85], v[88:89] op_sel_hi:[0,1,1]
	v_mov_b32_e32 v28, v27
	v_pk_fma_f32 v[32:33], v[68:69], v[26:27], 0 op_sel_hi:[0,1,0]
	v_pk_fma_f32 v[26:27], v[76:77], v[26:27], v[84:85] op_sel_hi:[0,1,1]
	v_lshlrev_b32_e32 v31, 16, v45
	v_mov_b32_e32 v30, v29
	v_pk_fma_f32 v[150:151], v[80:81], v[28:29], v[26:27] op_sel_hi:[0,1,1]
	v_pk_fma_f32 v[26:27], v[72:73], v[28:29], v[32:33] op_sel_hi:[0,1,1]
	v_lshlrev_b32_e32 v53, 16, v49
	v_mov_b32_e32 v52, v31
	v_pk_fma_f32 v[26:27], v[76:77], v[30:31], v[26:27] op_sel_hi:[0,1,1]
	v_pk_fma_f32 v[140:141], v[80:81], v[52:53], v[26:27] op_sel_hi:[0,1,1]
	v_and_b32_e32 v27, 0xffff0000, v59
	v_and_b32_e32 v26, 0xffff0000, v55
	v_and_b32_e32 v29, 0xffff0000, v83
	v_and_b32_e32 v28, 0xffff0000, v87
	v_mov_b32_e32 v32, v69
	v_lshlrev_b32_e32 v117, 16, v50
	v_and_b32_e32 v93, 0xffff0000, v50
	v_pk_fma_f32 v[84:85], v[32:33], v[28:29], 0 op_sel_hi:[0,1,0]
	v_mov_b32_e32 v50, v73
	v_pk_mov_b32 v[28:29], v[28:29], v[26:27] op_sel:[1,0]
	v_lshlrev_b32_e32 v116, 16, v46
	v_pk_fma_f32 v[28:29], v[50:51], v[28:29], v[84:85] op_sel_hi:[0,1,1]
	v_and_b32_e32 v143, 0xffff0000, v49
	v_and_b32_e32 v142, 0xffff0000, v45
	v_and_b32_e32 v153, 0xffff0000, v63
	v_mov_b32_e32 v152, v27
	v_pk_fma_f32 v[154:155], v[56:57], v[26:27], v[28:29] op_sel_hi:[0,1,1]
	v_pk_fma_f32 v[26:27], v[32:33], v[26:27], 0 op_sel_hi:[0,1,0]
	v_pk_mov_b32 v[124:125], v[134:135], v[116:117] op_sel:[1,0]
	v_pk_fma_f32 v[26:27], v[50:51], v[152:153], v[26:27] op_sel_hi:[0,1,1]
	v_pk_mov_b32 v[28:29], v[152:153], v[142:143] op_sel:[1,0]
	v_lshlrev_b32_e32 v109, 16, v40
	v_lshlrev_b32_e32 v108, 16, v36
	v_pk_fma_f32 v[146:147], v[56:57], v[28:29], v[26:27] op_sel_hi:[0,1,1]
	v_pk_fma_f32 v[26:27], v[14:15], v[124:125], 0 op_sel_hi:[0,1,0]
	v_pk_mov_b32 v[112:113], v[116:117], v[108:109] op_sel:[1,0]
	v_pk_fma_f32 v[110:111], v[2:3], v[116:117], v[26:27] op_sel_hi:[0,1,1]
	v_pk_fma_f32 v[26:27], v[14:15], v[112:113], 0 op_sel_hi:[0,1,0]
	v_pk_fma_f32 v[98:99], v[2:3], v[108:109], v[26:27] op_sel_hi:[0,1,1]
	v_and_b32_e32 v115, 0xffff0000, v39
	v_and_b32_e32 v114, 0xffff0000, v35
	v_pk_fma_f32 v[26:27], v[32:33], v[28:29], 0 op_sel_hi:[0,1,0]
	v_pk_fma_f32 v[26:27], v[50:51], v[142:143], v[26:27] op_sel_hi:[0,1,1]
	v_pk_mov_b32 v[28:29], v[142:143], v[114:115] op_sel:[1,0]
	s_waitcnt vmcnt(0) lgkmcnt(0)
; __device__ __forceinline__ float silu_f(float x) { return x * __builtin_amdgcn_rcpf(1.0f + __expf(-x)); }
; __device__ void prep_unit(unsigned char* lds, int bh, int n, const bf16_t* pc, const float* scal, const float* convw  , float alog, float dtb, unsigned char* unit, float* egl, unsigned* flag, unsigned fval) {
;     ...
; #pragma unroll
;         for (int i = 0; i < 11; ++i) { float xf[8]; unpack8(xr[i], xf);
; #pragma unroll
;             for (int t = 0; t < 8; ++t) { const int wi = i - t; if (wi >= 0 && wi < 4) {
; #pragma unroll
;                 for (int j = 0; j < 8; ++j) y[t][j] += w[wi][j] * xf[j]; } } }
;         float* XT = part == 0 ? qT : (part == 1 ? kT : vT);
;         float sq[8];
; #pragma unroll
;         for (int t = 0; t < 8; ++t) sq[t] = 0.f;
; #pragma unroll
;         for (int j = 0; j < 8; ++j) {
; #pragma unroll
;             for (int t = 0; t < 8; ++t) { y[t][j] = silu_f(y[t][j]); sq[t] += y[t][j] * y[t][j]; }
;             f32x4 a, c;
;             a[0] = y[0][j]; a[1] = y[1][j]; a[2] = y[2][j]; a[3] = y[3][j]; c[0] = y[4][j]; c[1] = y[5][j]; c[2] = y[6][j]; c[3] = y[7][j];
;             *(f32x4*)(XT + (cg8 * 8 + j) * 68 + run * 8) = a; *(f32x4*)(XT + (cg8 * 8 + j) * 68 + run * 8 + 4) = c;
	v_and_b32_e32 v95, 0xffff0000, v23
	v_and_b32_e32 v94, 0xffff0000, v19
	v_pk_fma_f32 v[118:119], v[56:57], v[28:29], v[26:27] op_sel_hi:[0,1,1]
	v_pk_fma_f32 v[26:27], v[32:33], v[28:29], 0 op_sel_hi:[0,1,0]
	v_pk_fma_f32 v[26:27], v[50:51], v[114:115], v[26:27] op_sel_hi:[0,1,1]
	v_pk_mov_b32 v[28:29], v[114:115], v[94:95] op_sel:[1,0]
	v_and_b32_e32 v92, 0xffff0000, v46
	v_pk_fma_f32 v[100:101], v[56:57], v[28:29], v[26:27] op_sel_hi:[0,1,1]
	v_lshlrev_b32_e32 v26, 16, v35
	v_lshlrev_b32_e32 v27, 16, v39
	v_pk_mov_b32 v[32:33], v[52:53], v[26:27] op_sel:[1,0]
	v_lshlrev_b32_e32 v29, 16, v19
	v_pk_fma_f32 v[148:149], v[68:69], v[32:33], 0 op_sel_hi:[0,1,0]
	v_lshlrev_b32_e32 v69, 16, v23
	v_pk_fma_f32 v[30:31], v[68:69], v[30:31], 0 op_sel_hi:[0,1,0]
	v_pk_fma_f32 v[30:31], v[72:73], v[52:53], v[30:31] op_sel_hi:[0,1,1]
	v_pk_fma_f32 v[30:31], v[76:77], v[32:33], v[30:31] op_sel_hi:[0,1,1]
	v_mov_b32_e32 v28, v27
	v_pk_fma_f32 v[122:123], v[80:81], v[26:27], v[30:31] op_sel_hi:[0,1,1]
	v_pk_fma_f32 v[26:27], v[72:73], v[26:27], v[148:149] op_sel_hi:[0,1,1]
	v_mov_b32_e32 v68, v29
	v_pk_fma_f32 v[26:27], v[76:77], v[28:29], v[26:27] op_sel_hi:[0,1,1]
	v_mov_b32_e32 v46, v81
	v_pk_fma_f32 v[80:81], v[80:81], v[68:69], v[26:27] op_sel_hi:[0,1,1]
	v_lshlrev_b32_e32 v27, 16, v82
	v_lshlrev_b32_e32 v26, 16, v86
	v_lshlrev_b32_e32 v28, 16, v54
	v_mov_b32_e32 v30, v27
	v_mov_b32_e32 v31, v28
	v_pk_fma_f32 v[26:27], v[66:67], v[26:27], 0 op_sel_hi:[0,1,0]
	v_lshlrev_b32_e32 v29, 16, v58
	v_pk_fma_f32 v[26:27], v[70:71], v[30:31], v[26:27] op_sel_hi:[0,1,1]
	v_lshlrev_b32_e32 v33, 16, v62
	v_mov_b32_e32 v32, v29
	v_pk_fma_f32 v[26:27], v[74:75], v[28:29], v[26:27] op_sel_hi:[0,1,1]
	v_pk_fma_f32 v[26:27], v[78:79], v[32:33], v[26:27] op_sel_hi:[0,1,1]
	v_mul_f32_e32 v19, 0xbfb8aa3b, v26
	v_exp_f32_e32 v19, v19
	v_pk_fma_f32 v[28:29], v[66:67], v[28:29], 0 op_sel_hi:[0,1,0]
	v_pk_fma_f32 v[28:29], v[70:71], v[32:33], v[28:29] op_sel_hi:[0,1,1]
	v_and_b32_e32 v55, 0xffff0000, v58
	v_add_f32_e32 v19, 1.0, v19
	v_rcp_f32_e32 v30, v19
	v_mul_f32_e32 v19, 0xbfb8aa3b, v27
	v_exp_f32_e32 v19, v19
	v_and_b32_e32 v59, 0xffff0000, v62
	v_mov_b32_e32 v58, v55
	v_and_b32_e32 v49, 0xffff0000, v48
	v_add_f32_e32 v19, 1.0, v19
	v_rcp_f32_e32 v31, v19
	v_and_b32_e32 v35, 0xffff0000, v38
	v_and_b32_e32 v88, 0xffff0000, v20
	v_lshlrev_b32_e32 v96, 16, v20
	v_pk_mul_f32 v[30:31], v[26:27], v[30:31]
	v_lshlrev_b32_e32 v27, 16, v48
	v_lshlrev_b32_e32 v26, 16, v44
	v_pk_mov_b32 v[52:53], v[32:33], v[26:27] op_sel:[1,0]
	v_and_b32_e32 v48, 0xffff0000, v44
	v_pk_fma_f32 v[28:29], v[74:75], v[52:53], v[28:29] op_sel_hi:[0,1,1]
	v_pk_fma_f32 v[28:29], v[78:79], v[26:27], v[28:29] op_sel_hi:[0,1,1]
	v_mul_f32_e32 v19, 0xbfb8aa3b, v28
	v_exp_f32_e32 v19, v19
	v_pk_fma_f32 v[52:53], v[66:67], v[52:53], 0 op_sel_hi:[0,1,0]
	v_and_b32_e32 v106, 0xffff0000, v60
	v_and_b32_e32 v107, 0xffff0000, v64
	v_add_f32_e32 v19, 1.0, v19
	v_rcp_f32_e32 v32, v19
	v_mul_f32_e32 v19, 0xbfb8aa3b, v29
	v_exp_f32_e32 v19, v19
	v_lshlrev_b32_e32 v105, 16, v61
	v_pk_mov_b32 v[62:63], v[130:131], v[106:107] op_sel:[1,0]
	v_and_b32_e32 v85, 0xffff0000, v40
	v_add_f32_e32 v19, 1.0, v19
	v_rcp_f32_e32 v33, v19
	v_mov_b32_e32 v40, v5
	v_lshlrev_b32_e32 v77, 16, v51
	v_lshlrev_b32_e32 v76, 16, v47
	v_pk_mul_f32 v[32:33], v[28:29], v[32:33]
	v_lshlrev_b32_e32 v29, 16, v38
	v_lshlrev_b32_e32 v28, 16, v34
	v_pk_mov_b32 v[68:69], v[26:27], v[28:29] op_sel:[1,0]
	v_pk_fma_f32 v[26:27], v[70:71], v[26:27], v[52:53] op_sel_hi:[0,1,1]
	v_pk_fma_f32 v[26:27], v[74:75], v[68:69], v[26:27] op_sel_hi:[0,1,1]
	v_pk_fma_f32 v[26:27], v[78:79], v[28:29], v[26:27] op_sel_hi:[0,1,1]
	v_mul_f32_e32 v19, 0xbfb8aa3b, v26
	v_exp_f32_e32 v19, v19
	v_pk_fma_f32 v[68:69], v[66:67], v[68:69], 0 op_sel_hi:[0,1,0]
	v_and_b32_e32 v34, 0xffff0000, v34
	v_and_b32_e32 v84, 0xffff0000, v36
	v_add_f32_e32 v19, 1.0, v19
	v_rcp_f32_e32 v52, v19
	v_mul_f32_e32 v19, 0xbfb8aa3b, v27
	v_exp_f32_e32 v19, v19
	v_lshlrev_b32_e32 v97, 16, v24
	v_pk_mov_b32 v[102:103], v[108:109], v[96:97] op_sel:[1,0]
	v_and_b32_e32 v89, 0xffff0000, v24
	v_add_f32_e32 v19, 1.0, v19
	v_rcp_f32_e32 v53, v19
	s_nop 0
	v_pk_mul_f32 v[26:27], v[26:27], v[52:53]
	v_lshlrev_b32_e32 v52, 16, v18
	v_lshlrev_b32_e32 v53, 16, v22
	v_pk_mov_b32 v[72:73], v[28:29], v[52:53] op_sel:[1,0]
	v_pk_fma_f32 v[28:29], v[70:71], v[28:29], v[68:69] op_sel_hi:[0,1,1]
	v_pk_fma_f32 v[28:29], v[74:75], v[72:73], v[28:29] op_sel_hi:[0,1,1]
	v_pk_fma_f32 v[28:29], v[78:79], v[52:53], v[28:29] op_sel_hi:[0,1,1]
	v_mul_f32_e32 v19, 0xbfb8aa3b, v28
	v_exp_f32_e32 v19, v19
	v_and_b32_e32 v18, 0xffff0000, v18
	v_add_f32_e32 v19, 1.0, v19
	v_rcp_f32_e32 v52, v19
	v_mul_f32_e32 v19, 0xbfb8aa3b, v29
	v_exp_f32_e32 v19, v19
	s_nop 0
	v_add_f32_e32 v19, 1.0, v19
	v_rcp_f32_e32 v53, v19
	v_mul_u32_u24_e32 v19, 0x110, v42
	v_add3_u32 v83, v43, v158, v19
	v_and_b32_e32 v43, 0xffff0000, v82
	v_and_b32_e32 v42, 0xffff0000, v86
	v_pk_mul_f32 v[28:29], v[28:29], v[52:53]
	v_and_b32_e32 v53, 0xffff0000, v54
	v_mov_b32_e32 v52, v43
	v_pk_fma_f32 v[42:43], v[66:67], v[42:43], 0 op_sel:[1,0,0] op_sel_hi:[1,1,0]
	v_mov_b32_e32 v54, v53
	v_pk_fma_f32 v[42:43], v[70:71], v[52:53], v[42:43] op_sel:[1,0,0]
	v_pk_fma_f32 v[44:45], v[66:67], v[54:55], 0 op_sel:[1,0,0] op_sel_hi:[1,1,0]
	v_pk_fma_f32 v[42:43], v[74:75], v[54:55], v[42:43] op_sel:[1,0,0]
	v_pk_fma_f32 v[44:45], v[70:71], v[58:59], v[44:45] op_sel:[1,0,0]
	v_pk_fma_f32 v[42:43], v[78:79], v[58:59], v[42:43] op_sel:[1,0,0]
	v_mov_b32_e32 v86, v17
	v_mul_f32_e32 v19, 0xbfb8aa3b, v42
	v_exp_f32_e32 v19, v19
	v_mov_b32_e32 v82, v13
	ds_write_b128 v83, v[30:33]
; __device__ __forceinline__ float silu_f(float x) { return x * __builtin_amdgcn_rcpf(1.0f + __expf(-x)); }
; __device__ void prep_unit(unsigned char* lds, int bh, int n, const bf16_t* pc, const float* scal, const float* convw  , float alog, float dtb, unsigned char* unit, float* egl, unsigned* flag, unsigned fval) {
;     ...
;         for (int j = 0; j < 8; ++j) {
; #pragma unroll
;             for (int t = 0; t < 8; ++t) { y[t][j] = silu_f(y[t][j]); sq[t] += y[t][j] * y[t][j]; }
;             f32x4 a, c;
;             a[0] = y[0][j]; a[1] = y[1][j]; a[2] = y[2][j]; a[3] = y[3][j]; c[0] = y[4][j]; c[1] = y[5][j]; c[2] = y[6][j]; c[3] = y[7][j];
;             *(f32x4*)(XT + (cg8 * 8 + j) * 68 + run * 8) = a; *(f32x4*)(XT + (cg8 * 8 + j) * 68 + run * 8 + 4) = c;
	ds_write_b128 v83, v[26:29] offset:16
	v_add_f32_e32 v19, 1.0, v19
	v_rcp_f32_e32 v52, v19
	v_mul_f32_e32 v19, 0xbfb8aa3b, v43
	v_exp_f32_e32 v19, v19
	s_nop 0
	v_add_f32_e32 v19, 1.0, v19
	v_rcp_f32_e32 v53, v19
	s_nop 0
	v_pk_mul_f32 v[42:43], v[42:43], v[52:53]
	v_pk_mov_b32 v[52:53], v[58:59], v[48:49] op_sel:[1,0]
	v_pk_fma_f32 v[58:59], v[2:3], v[130:131], v[136:137] op_sel:[1,0,0]
	v_pk_fma_f32 v[44:45], v[74:75], v[52:53], v[44:45] op_sel:[1,0,0]
	v_pk_fma_f32 v[38:39], v[66:67], v[52:53], 0 op_sel:[1,0,0] op_sel_hi:[1,1,0]
	v_pk_fma_f32 v[44:45], v[78:79], v[48:49], v[44:45] op_sel:[1,0,0]
	v_pk_fma_f32 v[38:39], v[70:71], v[48:49], v[38:39] op_sel:[1,0,0]
	v_mul_f32_e32 v19, 0xbfb8aa3b, v44
	v_exp_f32_e32 v19, v19
	v_pk_fma_f32 v[58:59], v[6:7], v[62:63], v[58:59] op_sel:[1,0,0]
	v_add_f32_e32 v19, 1.0, v19
	v_rcp_f32_e32 v54, v19
	v_mul_f32_e32 v19, 0xbfb8aa3b, v45
	v_exp_f32_e32 v19, v19
	v_pk_fma_f32 v[58:59], v[10:11], v[106:107], v[58:59] op_sel:[1,0,0]
	v_add_f32_e32 v19, 1.0, v19
	v_rcp_f32_e32 v55, v19
	s_nop 0
	v_pk_mul_f32 v[44:45], v[44:45], v[54:55]
	v_pk_mov_b32 v[54:55], v[48:49], v[34:35] op_sel:[1,0]
	s_nop 0
	v_pk_fma_f32 v[38:39], v[74:75], v[54:55], v[38:39] op_sel:[1,0,0]
	s_nop 0
	v_pk_fma_f32 v[38:39], v[78:79], v[34:35], v[38:39] op_sel:[1,0,0]
	s_nop 0
	v_mul_f32_e32 v19, 0xbfb8aa3b, v38
	v_exp_f32_e32 v19, v19
	s_nop 0
	v_add_f32_e32 v19, 1.0, v19
	v_rcp_f32_e32 v48, v19
	v_mul_f32_e32 v19, 0xbfb8aa3b, v39
	v_exp_f32_e32 v19, v19
	s_nop 0
	v_add_f32_e32 v19, 1.0, v19
	v_rcp_f32_e32 v49, v19
	v_and_b32_e32 v19, 0xffff0000, v22
	v_pk_fma_f32 v[22:23], v[66:67], v[54:55], 0 op_sel:[1,0,0] op_sel_hi:[1,1,0]
	v_lshlrev_b32_e32 v67, 16, v65
	v_pk_mul_f32 v[52:53], v[38:39], v[48:49]
	v_pk_mov_b32 v[38:39], v[34:35], v[18:19] op_sel:[1,0]
	v_pk_fma_f32 v[22:23], v[70:71], v[34:35], v[22:23] op_sel:[1,0,0]
	v_pk_fma_f32 v[48:49], v[16:17], v[132:133], 0 op_sel_hi:[0,1,0]
	v_pk_fma_f32 v[22:23], v[74:75], v[38:39], v[22:23] op_sel:[1,0,0]
	v_pk_fma_f32 v[74:75], v[14:15], v[62:63], 0 op_sel:[1,0,0] op_sel_hi:[1,1,0]
	v_pk_fma_f32 v[18:19], v[78:79], v[18:19], v[22:23] op_sel:[1,0,0]
	v_pk_fma_f32 v[62:63], v[46:47], v[152:153], v[154:155] op_sel_hi:[0,1,1]
	v_mul_f32_e32 v20, 0xbfb8aa3b, v18
	v_exp_f32_e32 v20, v20
	v_mov_b32_e32 v66, v105
	v_mov_b32_e32 v78, v9
	v_and_b32_e32 v71, 0xffff0000, v65
	v_add_f32_e32 v20, 1.0, v20
	v_rcp_f32_e32 v22, v20
	v_mul_f32_e32 v20, 0xbfb8aa3b, v19
	v_exp_f32_e32 v20, v20
	v_pk_fma_f32 v[74:75], v[2:3], v[106:107], v[74:75] op_sel:[1,0,0]
	v_add_f32_e32 v20, 1.0, v20
	v_rcp_f32_e32 v23, v20
	v_mul_f32_e32 v20, 0xbfb8aa3b, v80
	v_exp_f32_e32 v20, v20
	v_pk_mul_f32 v[54:55], v[18:19], v[22:23]
	v_mul_f32_e32 v18, 0xbfb8aa3b, v150
	v_exp_f32_e32 v18, v18
	v_and_b32_e32 v23, 0xffff0000, v61
	v_pk_mov_b32 v[60:61], v[132:133], v[104:105] op_sel:[1,0]
	v_and_b32_e32 v22, 0xffff0000, v57
	v_add_f32_e32 v18, 1.0, v18
	v_rcp_f32_e32 v38, v18
	v_mul_f32_e32 v18, 0xbfb8aa3b, v151
	v_exp_f32_e32 v18, v18
	v_pk_fma_f32 v[48:49], v[4:5], v[60:61], v[48:49] op_sel_hi:[0,1,1]
	v_mul_f32_e32 v5, 0xbfb8aa3b, v62
	v_exp_f32_e32 v5, v5
	v_add_f32_e32 v18, 1.0, v18
	v_rcp_f32_e32 v39, v18
	v_pk_fma_f32 v[48:49], v[8:9], v[104:105], v[48:49] op_sel_hi:[0,1,1]
	v_add_f32_e32 v5, 1.0, v5
	v_pk_fma_f32 v[68:69], v[12:13], v[66:67], v[48:49] op_sel_hi:[0,1,1]
	v_pk_mul_f32 v[48:49], v[150:151], v[38:39]
	v_rcp_f32_e32 v38, v5
	v_mul_f32_e32 v5, 0xbfb8aa3b, v63
	v_exp_f32_e32 v5, v5
	v_pk_fma_f32 v[60:61], v[6:7], v[138:139], v[144:145] op_sel_hi:[0,1,1]
	v_pk_fma_f32 v[60:61], v[10:11], v[134:135], v[60:61] op_sel_hi:[0,1,1]
	v_mov_b32_e32 v129, v22
	v_add_f32_e32 v5, 1.0, v5
	v_rcp_f32_e32 v39, v5
	v_mul_f32_e32 v5, 0xbfb8aa3b, v60
	v_exp_f32_e32 v5, v5
	v_pk_fma_f32 v[56:57], v[86:87], v[126:127], 0 op_sel_hi:[0,1,0]
	v_pk_fma_f32 v[56:57], v[40:41], v[128:129], v[56:57] op_sel_hi:[0,1,1]
	v_mov_b32_e32 v70, v23
	v_pk_fma_f32 v[56:57], v[78:79], v[22:23], v[56:57] op_sel_hi:[0,1,1]
	v_add_f32_e32 v5, 1.0, v5
	v_pk_fma_f32 v[72:73], v[82:83], v[70:71], v[56:57] op_sel_hi:[0,1,1]
	v_pk_mul_f32 v[56:57], v[62:63], v[38:39]
	v_rcp_f32_e32 v38, v5
	v_mul_f32_e32 v5, 0xbfb8aa3b, v61
	v_exp_f32_e32 v5, v5
	v_mul_f32_e32 v18, 0xbfb8aa3b, v140
	v_exp_f32_e32 v18, v18
	v_pk_fma_f32 v[62:63], v[46:47], v[142:143], v[146:147] op_sel_hi:[0,1,1]
	v_add_f32_e32 v5, 1.0, v5
	v_rcp_f32_e32 v39, v5
	v_mul_f32_e32 v5, 0xbfb8aa3b, v58
	v_exp_f32_e32 v5, v5
	v_add_f32_e32 v18, 1.0, v18
	v_pk_mul_f32 v[60:61], v[60:61], v[38:39]
	v_rcp_f32_e32 v34, v18
	v_add_f32_e32 v5, 1.0, v5
	v_rcp_f32_e32 v38, v5
	v_mul_f32_e32 v5, 0xbfb8aa3b, v59
	v_exp_f32_e32 v5, v5
	v_mul_f32_e32 v18, 0xbfb8aa3b, v141
	v_exp_f32_e32 v18, v18
	v_pk_mov_b32 v[126:127], v[106:107], v[92:93] op_sel:[1,0]
	v_add_f32_e32 v5, 1.0, v5
	v_rcp_f32_e32 v39, v5
	v_mul_f32_e32 v5, 0xbfb8aa3b, v68
	v_exp_f32_e32 v5, v5
	v_add_f32_e32 v18, 1.0, v18
	v_pk_mul_f32 v[64:65], v[58:59], v[38:39]
	v_rcp_f32_e32 v35, v18
	v_add_f32_e32 v5, 1.0, v5
	v_rcp_f32_e32 v38, v5
	v_mul_f32_e32 v5, 0xbfb8aa3b, v69
	v_exp_f32_e32 v5, v5
	v_pk_fma_f32 v[58:59], v[6:7], v[124:125], v[120:121] op_sel_hi:[0,1,1]
	v_pk_fma_f32 v[116:117], v[10:11], v[116:117], v[58:59] op_sel_hi:[0,1,1]
	v_pk_mov_b32 v[124:125], v[66:67], v[76:77] op_sel:[1,0]
	v_add_f32_e32 v5, 1.0, v5
	v_rcp_f32_e32 v39, v5
	v_mul_f32_e32 v5, 0xbfb8aa3b, v72
	v_exp_f32_e32 v5, v5
	v_pk_fma_f32 v[22:23], v[86:87], v[22:23], 0 op_sel_hi:[0,1,0]
	v_pk_mul_f32 v[68:69], v[68:69], v[38:39]
	v_pk_fma_f32 v[22:23], v[40:41], v[70:71], v[22:23] op_sel_hi:[0,1,1]
	v_add_f32_e32 v5, 1.0, v5
	v_rcp_f32_e32 v38, v5
; __device__ __forceinline__ float silu_f(float x) { return x * __builtin_amdgcn_rcpf(1.0f + __expf(-x)); }
; __device__ void prep_unit(unsigned char* lds, int bh, int n, const bf16_t* pc, const float* scal, const float* convw  , float alog, float dtb, unsigned char* unit, float* egl, unsigned* flag, unsigned fval) {
;     ...
;         for (int j = 0; j < 8; ++j) {
; #pragma unroll
;             for (int t = 0; t < 8; ++t) { y[t][j] = silu_f(y[t][j]); sq[t] += y[t][j] * y[t][j]; }
;             f32x4 a, c;
;             a[0] = y[0][j]; a[1] = y[1][j]; a[2] = y[2][j]; a[3] = y[3][j]; c[0] = y[4][j]; c[1] = y[5][j]; c[2] = y[6][j]; c[3] = y[7][j];
;             *(f32x4*)(XT + (cg8 * 8 + j) * 68 + run * 8) = a; *(f32x4*)(XT + (cg8 * 8 + j) * 68 + run * 8 + 4) = c;
	v_mul_f32_e32 v5, 0xbfb8aa3b, v73
	v_exp_f32_e32 v5, v5
	v_lshlrev_b32_e32 v106, 16, v37
	v_pk_fma_f32 v[120:121], v[14:15], v[126:127], 0 op_sel:[1,0,0] op_sel_hi:[1,1,0]
	v_lshlrev_b32_e32 v107, 16, v41
	v_add_f32_e32 v5, 1.0, v5
	v_rcp_f32_e32 v39, v5
	v_mul_f32_e32 v5, 0xbfb8aa3b, v62
	v_exp_f32_e32 v5, v5
	v_add_f32_e32 v20, 1.0, v20
	v_pk_mul_f32 v[72:73], v[72:73], v[38:39]
	v_and_b32_e32 v39, 0xffff0000, v51
	v_add_f32_e32 v5, 1.0, v5
	v_pk_mul_f32 v[50:51], v[140:141], v[34:35]
	v_rcp_f32_e32 v34, v5
	v_mul_f32_e32 v5, 0xbfb8aa3b, v63
	v_exp_f32_e32 v5, v5
	v_and_b32_e32 v38, 0xffff0000, v47
	v_rcp_f32_e32 v148, v20
	v_mul_f32_e32 v20, 0xbfb8aa3b, v81
	v_add_f32_e32 v5, 1.0, v5
	v_rcp_f32_e32 v35, v5
	v_mul_f32_e32 v5, 0xbfb8aa3b, v116
	v_exp_f32_e32 v5, v5
	v_exp_f32_e32 v20, v20
	v_pk_mul_f32 v[58:59], v[62:63], v[34:35]
	v_mul_f32_e32 v18, 0xbfb8aa3b, v122
	v_add_f32_e32 v5, 1.0, v5
	v_rcp_f32_e32 v34, v5
	v_mul_f32_e32 v5, 0xbfb8aa3b, v117
	v_exp_f32_e32 v5, v5
	v_add_f32_e32 v20, 1.0, v20
	v_rcp_f32_e32 v149, v20
	v_mul_f32_e32 v19, 0xbfb8aa3b, v123
	v_add_f32_e32 v5, 1.0, v5
	v_rcp_f32_e32 v35, v5
	v_exp_f32_e32 v18, v18
	v_exp_f32_e32 v19, v19
	ds_write_b128 v83, v[42:45] offset:272
	ds_write_b128 v83, v[52:55] offset:288
	v_pk_mul_f32 v[62:63], v[116:117], v[34:35]
	v_pk_fma_f32 v[34:35], v[16:17], v[104:105], 0 op_sel_hi:[0,1,0]
	v_pk_fma_f32 v[34:35], v[4:5], v[66:67], v[34:35] op_sel_hi:[0,1,1]
	v_pk_fma_f32 v[66:67], v[6:7], v[126:127], v[74:75] op_sel:[1,0,0]
	v_pk_mov_b32 v[116:117], v[70:71], v[38:39] op_sel:[1,0]
	v_pk_fma_f32 v[66:67], v[10:11], v[92:93], v[66:67] op_sel:[1,0,0]
	v_pk_fma_f32 v[34:35], v[8:9], v[124:125], v[34:35] op_sel_hi:[0,1,1]
	v_mul_f32_e32 v5, 0xbfb8aa3b, v66
	v_exp_f32_e32 v5, v5
	v_pk_fma_f32 v[34:35], v[12:13], v[76:77], v[34:35] op_sel_hi:[0,1,1]
	v_pk_fma_f32 v[22:23], v[78:79], v[116:117], v[22:23] op_sel_hi:[0,1,1]
	v_pk_fma_f32 v[22:23], v[82:83], v[38:39], v[22:23] op_sel_hi:[0,1,1]
	v_add_f32_e32 v5, 1.0, v5
	v_rcp_f32_e32 v70, v5
	v_mul_f32_e32 v5, 0xbfb8aa3b, v67
	v_exp_f32_e32 v5, v5
	v_and_b32_e32 v104, 0xffff0000, v37
	v_pk_mov_b32 v[36:37], v[92:93], v[84:85] op_sel:[1,0]
	v_pk_fma_f32 v[92:93], v[2:3], v[92:93], v[120:121] op_sel:[1,0,0]
	v_add_f32_e32 v5, 1.0, v5
	v_rcp_f32_e32 v71, v5
	v_mul_f32_e32 v5, 0xbfb8aa3b, v34
	v_exp_f32_e32 v5, v5
	v_and_b32_e32 v105, 0xffff0000, v41
	v_pk_mul_f32 v[66:67], v[66:67], v[70:71]
	v_add_f32_e32 v18, 1.0, v18
	v_add_f32_e32 v5, 1.0, v5
	v_rcp_f32_e32 v70, v5
	v_mul_f32_e32 v5, 0xbfb8aa3b, v35
	v_exp_f32_e32 v5, v5
	v_add_f32_e32 v19, 1.0, v19
	v_rcp_f32_e32 v18, v18
	v_rcp_f32_e32 v19, v19
	v_add_f32_e32 v5, 1.0, v5
	v_rcp_f32_e32 v71, v5
	v_mul_f32_e32 v5, 0xbfb8aa3b, v22
	v_exp_f32_e32 v5, v5
	v_pk_mul_f32 v[18:19], v[122:123], v[18:19]
	v_pk_mul_f32 v[70:71], v[34:35], v[70:71]
	ds_write_b128 v83, v[48:51] offset:544
	ds_write_b128 v83, v[56:59] offset:816
	ds_write_b128 v83, v[60:63] offset:1088
	v_add_f32_e32 v5, 1.0, v5
	v_rcp_f32_e32 v34, v5
	v_mul_f32_e32 v5, 0xbfb8aa3b, v23
	v_exp_f32_e32 v5, v5
	ds_write_b128 v83, v[64:67] offset:1360
	ds_write_b128 v83, v[68:71] offset:1632
	v_add_f32_e32 v5, 1.0, v5
	v_rcp_f32_e32 v35, v5
	s_nop 0
	v_pk_mul_f32 v[74:75], v[22:23], v[34:35]
	v_pk_fma_f32 v[22:23], v[6:7], v[112:113], v[110:111] op_sel_hi:[0,1,1]
	v_pk_fma_f32 v[110:111], v[14:15], v[36:37], 0 op_sel:[1,0,0] op_sel_hi:[1,1,0]
	v_pk_fma_f32 v[14:15], v[46:47], v[114:115], v[118:119] op_sel_hi:[0,1,1]
	v_mul_f32_e32 v5, 0xbfb8aa3b, v14
	v_exp_f32_e32 v5, v5
	v_pk_fma_f32 v[34:35], v[10:11], v[108:109], v[22:23] op_sel_hi:[0,1,1]
	v_pk_fma_f32 v[36:37], v[6:7], v[36:37], v[92:93] op_sel:[1,0,0]
	v_pk_mov_b32 v[112:113], v[76:77], v[106:107] op_sel:[1,0]
	v_add_f32_e32 v5, 1.0, v5
	v_rcp_f32_e32 v22, v5
	v_mul_f32_e32 v5, 0xbfb8aa3b, v15
	v_exp_f32_e32 v5, v5
	v_pk_fma_f32 v[36:37], v[10:11], v[84:85], v[36:37] op_sel:[1,0,0]
	v_pk_fma_f32 v[108:109], v[86:87], v[116:117], 0 op_sel_hi:[0,1,0]
	v_pk_mov_b32 v[114:115], v[38:39], v[104:105] op_sel:[1,0]
	v_add_f32_e32 v5, 1.0, v5
	v_rcp_f32_e32 v23, v5
	v_mul_f32_e32 v5, 0xbfb8aa3b, v34
	v_exp_f32_e32 v5, v5
	v_pk_fma_f32 v[2:3], v[2:3], v[84:85], v[110:111] op_sel:[1,0,0]
	v_pk_mul_f32 v[22:23], v[14:15], v[22:23]
	v_add_f32_e32 v5, 1.0, v5
	v_rcp_f32_e32 v14, v5
	v_mul_f32_e32 v5, 0xbfb8aa3b, v35
	v_exp_f32_e32 v5, v5
	s_nop 0
	v_add_f32_e32 v5, 1.0, v5
	v_rcp_f32_e32 v15, v5
	v_mul_f32_e32 v5, 0xbfb8aa3b, v37
	v_exp_f32_e32 v5, v5
	v_pk_mul_f32 v[34:35], v[34:35], v[14:15]
	v_pk_fma_f32 v[14:15], v[16:17], v[124:125], 0 op_sel_hi:[0,1,0]
	v_add_f32_e32 v5, 1.0, v5
	v_pk_fma_f32 v[14:15], v[4:5], v[76:77], v[14:15] op_sel_hi:[0,1,1]
	v_pk_fma_f32 v[14:15], v[8:9], v[112:113], v[14:15] op_sel_hi:[0,1,1]
	v_pk_fma_f32 v[76:77], v[12:13], v[106:107], v[14:15] op_sel_hi:[0,1,1]
	v_rcp_f32_e32 v93, v5
	v_mul_f32_e32 v5, 0xbfb8aa3b, v77
	v_exp_f32_e32 v5, v5
	v_pk_fma_f32 v[14:15], v[40:41], v[38:39], v[108:109] op_sel_hi:[0,1,1]
	v_pk_fma_f32 v[14:15], v[78:79], v[114:115], v[14:15] op_sel_hi:[0,1,1]
	v_pk_fma_f32 v[108:109], v[82:83], v[104:105], v[14:15] op_sel_hi:[0,1,1]
	v_add_f32_e32 v5, 1.0, v5
	v_rcp_f32_e32 v117, v5
	v_mul_f32_e32 v5, 0xbfb8aa3b, v36
	v_exp_f32_e32 v5, v5
	v_pk_fma_f32 v[16:17], v[16:17], v[112:113], 0 op_sel_hi:[0,1,0]
	v_add_f32_e32 v5, 1.0, v5
	v_rcp_f32_e32 v92, v5
	v_mul_f32_e32 v5, 0xbfb8aa3b, v76
	v_exp_f32_e32 v5, v5
	v_pk_mul_f32 v[14:15], v[36:37], v[92:93]
	v_lshlrev_b32_e32 v93, 16, v25
	v_add_f32_e32 v5, 1.0, v5
	v_rcp_f32_e32 v116, v5
	v_mul_f32_e32 v5, 0xbfb8aa3b, v108
	v_exp_f32_e32 v5, v5
	v_lshlrev_b32_e32 v92, 16, v21
; __device__ __forceinline__ float silu_f(float x) { return x * __builtin_amdgcn_rcpf(1.0f + __expf(-x)); }
; __device__ void prep_unit(unsigned char* lds, int bh, int n, const bf16_t* pc, const float* scal, const float* convw  , float alog, float dtb, unsigned char* unit, float* egl, unsigned* flag, unsigned fval) {
;     ...
;         for (int j = 0; j < 8; ++j) {
; #pragma unroll
;             for (int t = 0; t < 8; ++t) { y[t][j] = silu_f(y[t][j]); sq[t] += y[t][j] * y[t][j]; }
;             f32x4 a, c;
;             a[0] = y[0][j]; a[1] = y[1][j]; a[2] = y[2][j]; a[3] = y[3][j]; c[0] = y[4][j]; c[1] = y[5][j]; c[2] = y[6][j]; c[3] = y[7][j];
;             *(f32x4*)(XT + (cg8 * 8 + j) * 68 + run * 8) = a; *(f32x4*)(XT + (cg8 * 8 + j) * 68 + run * 8 + 4) = c;
;         }
;         if (part < 2) {
; #pragma unroll
;             for (int t = 0; t < 8; ++t) { float v = sq[t]; v += __shfl_xor(v, 8); v += __shfl_xor(v, 16); v += __shfl_xor(v, 32); sq[t] = v; }
;             if ((lane >> 3) == 0) {
; #pragma unroll
;                 for (int t = 0; t < 8; ++t) ssp[(part * 2 + (wid & 1)) * 64 + run * 8 + t] = sq[t];
;             }
;         }
	v_pk_mul_f32 v[38:39], v[76:77], v[116:117]
	v_add_f32_e32 v5, 1.0, v5
	v_rcp_f32_e32 v36, v5
	v_mul_f32_e32 v5, 0xbfb8aa3b, v109
	v_exp_f32_e32 v5, v5
	s_nop 0
	v_add_f32_e32 v5, 1.0, v5
	v_rcp_f32_e32 v37, v5
	s_nop 0
	v_pk_mul_f32 v[76:77], v[108:109], v[36:37]
	v_pk_fma_f32 v[36:37], v[6:7], v[102:103], v[98:99] op_sel_hi:[0,1,1]
	v_and_b32_e32 v99, 0xffff0000, v25
	v_pk_fma_f32 v[24:25], v[46:47], v[94:95], v[100:101] op_sel_hi:[0,1,1]
	v_mul_f32_e32 v5, 0xbfb8aa3b, v24
	v_exp_f32_e32 v5, v5
	v_pk_fma_f32 v[36:37], v[10:11], v[96:97], v[36:37] op_sel_hi:[0,1,1]
	v_and_b32_e32 v98, 0xffff0000, v21
	v_pk_mul_f32 v[20:21], v[80:81], v[148:149]
	v_add_f32_e32 v5, 1.0, v5
	v_rcp_f32_e32 v46, v5
	v_mul_f32_e32 v5, 0xbfb8aa3b, v25
	v_exp_f32_e32 v5, v5
	v_pk_mov_b32 v[80:81], v[84:85], v[88:89] op_sel:[1,0]
	v_pk_mov_b32 v[94:95], v[104:105], v[98:99] op_sel:[1,0]
	v_pk_fma_f32 v[2:3], v[6:7], v[80:81], v[2:3] op_sel:[1,0,0]
	v_add_f32_e32 v5, 1.0, v5
	v_rcp_f32_e32 v47, v5
	v_mul_f32_e32 v5, 0xbfb8aa3b, v36
	v_exp_f32_e32 v5, v5
	v_pk_fma_f32 v[2:3], v[10:11], v[88:89], v[2:3] op_sel:[1,0,0]
	v_pk_mul_f32 v[24:25], v[24:25], v[46:47]
	v_add_f32_e32 v5, 1.0, v5
	v_rcp_f32_e32 v46, v5
	v_mul_f32_e32 v5, 0xbfb8aa3b, v37
	v_exp_f32_e32 v5, v5
	s_nop 0
	v_add_f32_e32 v5, 1.0, v5
	v_rcp_f32_e32 v47, v5
	v_mul_f32_e32 v5, 0xbfb8aa3b, v3
	v_exp_f32_e32 v5, v5
	v_pk_mul_f32 v[36:37], v[36:37], v[46:47]
	v_pk_fma_f32 v[46:47], v[86:87], v[114:115], 0 op_sel_hi:[0,1,0]
	v_add_f32_e32 v5, 1.0, v5
	v_rcp_f32_e32 v5, v5
	v_pk_mov_b32 v[86:87], v[106:107], v[92:93] op_sel:[1,0]
	v_pk_fma_f32 v[10:11], v[40:41], v[104:105], v[46:47] op_sel_hi:[0,1,1]
	v_pk_fma_f32 v[10:11], v[78:79], v[94:95], v[10:11] op_sel_hi:[0,1,1]
	v_pk_fma_f32 v[6:7], v[4:5], v[106:107], v[16:17] op_sel_hi:[0,1,1]
	v_pk_fma_f32 v[6:7], v[8:9], v[86:87], v[6:7] op_sel_hi:[0,1,1]
	v_pk_fma_f32 v[6:7], v[12:13], v[92:93], v[6:7] op_sel_hi:[0,1,1]
	v_mul_f32_e32 v4, 0xbfb8aa3b, v7
	v_exp_f32_e32 v4, v4
	v_pk_fma_f32 v[10:11], v[82:83], v[98:99], v[10:11] op_sel_hi:[0,1,1]
	ds_write_b128 v83, v[18:21] offset:560
	ds_write_b128 v83, v[22:25] offset:832
	ds_write_b128 v83, v[34:37] offset:1104
	v_add_f32_e32 v4, 1.0, v4
	v_rcp_f32_e32 v9, v4
	v_mul_f32_e32 v4, 0xbfb8aa3b, v2
	v_exp_f32_e32 v4, v4
	s_nop 0
	v_add_f32_e32 v4, 1.0, v4
	v_rcp_f32_e32 v4, v4
	s_nop 0
	v_pk_mul_f32 v[16:17], v[2:3], v[4:5]
	v_mul_f32_e32 v2, 0xbfb8aa3b, v6
	v_exp_f32_e32 v2, v2
	v_mul_f32_e32 v3, 0xbfb8aa3b, v11
	v_exp_f32_e32 v3, v3
	v_add_f32_e32 v2, 1.0, v2
	v_rcp_f32_e32 v8, v2
	v_mul_f32_e32 v2, 0xbfb8aa3b, v10
	v_exp_f32_e32 v2, v2
	v_add_f32_e32 v3, 1.0, v3
	v_rcp_f32_e32 v3, v3
	v_pk_mul_f32 v[40:41], v[6:7], v[8:9]
	v_add_f32_e32 v2, 1.0, v2
	v_rcp_f32_e32 v2, v2
	ds_write_b128 v83, v[14:17] offset:1376
	ds_write_b128 v83, v[38:41] offset:1648
	v_pk_mul_f32 v[78:79], v[10:11], v[2:3]
	ds_write_b128 v83, v[72:75] offset:1904
	ds_write_b128 v83, v[76:79] offset:1920
	s_and_saveexec_b64 s[2:3], vcc
	s_cbranch_execz .LBB0_317
	v_pk_mul_f32 v[10:11], v[52:53], v[52:53]
	v_and_b32_e32 v5, 64, v218
	v_pk_fma_f32 v[10:11], v[26:27], v[26:27], v[10:11]
	v_xor_b32_e32 v4, 8, v218
	v_pk_fma_f32 v[10:11], v[18:19], v[18:19], v[10:11]
	v_add_u32_e32 v5, 64, v5
	v_pk_fma_f32 v[10:11], v[22:23], v[22:23], v[10:11]
	v_pk_mul_f32 v[46:47], v[54:55], v[54:55]
	v_pk_mul_f32 v[6:7], v[44:45], v[44:45]
	v_pk_mul_f32 v[2:3], v[42:43], v[42:43]
	v_cmp_lt_i32_e32 vcc, v4, v5
	v_pk_fma_f32 v[10:11], v[34:35], v[34:35], v[10:11]
	v_pk_fma_f32 v[2:3], v[30:31], v[30:31], v[2:3]
	v_cndmask_b32_e32 v4, v218, v4, vcc
	v_pk_fma_f32 v[6:7], v[32:33], v[32:33], v[6:7]
	v_pk_fma_f32 v[10:11], v[14:15], v[14:15], v[10:11]
	v_pk_fma_f32 v[14:15], v[28:29], v[28:29], v[46:47]
	v_lshlrev_b32_e32 v42, 2, v4
	v_xor_b32_e32 v4, 16, v218
	v_pk_fma_f32 v[2:3], v[48:49], v[48:49], v[2:3]
	v_pk_fma_f32 v[6:7], v[50:51], v[50:51], v[6:7]
	v_pk_fma_f32 v[14:15], v[20:21], v[20:21], v[14:15]
	v_cmp_lt_i32_e32 vcc, v4, v5
	v_pk_fma_f32 v[2:3], v[56:57], v[56:57], v[2:3]
	v_pk_fma_f32 v[6:7], v[58:59], v[58:59], v[6:7]
	v_pk_fma_f32 v[14:15], v[24:25], v[24:25], v[14:15]
	v_cndmask_b32_e32 v4, v218, v4, vcc
	v_pk_fma_f32 v[2:3], v[60:61], v[60:61], v[2:3]
	v_pk_fma_f32 v[6:7], v[62:63], v[62:63], v[6:7]
	v_pk_fma_f32 v[14:15], v[36:37], v[36:37], v[14:15]
	v_lshlrev_b32_e32 v43, 2, v4
	v_xor_b32_e32 v4, 32, v218
	v_pk_fma_f32 v[2:3], v[64:65], v[64:65], v[2:3]
	v_pk_fma_f32 v[6:7], v[66:67], v[66:67], v[6:7]
	v_pk_fma_f32 v[14:15], v[16:17], v[16:17], v[14:15]
	v_cmp_lt_i32_e32 vcc, v4, v5
	v_pk_fma_f32 v[2:3], v[68:69], v[68:69], v[2:3]
	v_pk_fma_f32 v[6:7], v[70:71], v[70:71], v[6:7]
	v_pk_fma_f32 v[10:11], v[38:39], v[38:39], v[10:11]
	v_pk_fma_f32 v[14:15], v[40:41], v[40:41], v[14:15]
	v_cndmask_b32_e32 v4, v218, v4, vcc
	v_pk_fma_f32 v[2:3], v[72:73], v[72:73], v[2:3]
	v_pk_fma_f32 v[6:7], v[74:75], v[74:75], v[6:7]
	v_pk_fma_f32 v[10:11], v[76:77], v[76:77], v[10:11]
	v_pk_fma_f32 v[14:15], v[78:79], v[78:79], v[14:15]
	v_lshlrev_b32_e32 v44, 2, v4
	ds_bpermute_b32 v4, v42, v2
	ds_bpermute_b32 v5, v42, v3
	ds_bpermute_b32 v8, v42, v6
	ds_bpermute_b32 v9, v42, v7
	ds_bpermute_b32 v12, v42, v10
	ds_bpermute_b32 v13, v42, v11
	ds_bpermute_b32 v16, v42, v14
	ds_bpermute_b32 v17, v42, v15
	s_waitcnt lgkmcnt(6)
	v_pk_add_f32 v[2:3], v[2:3], v[4:5]
	s_waitcnt lgkmcnt(4)
	v_pk_add_f32 v[6:7], v[6:7], v[8:9]
	s_waitcnt lgkmcnt(2)
	v_pk_add_f32 v[10:11], v[10:11], v[12:13]
	ds_bpermute_b32 v4, v43, v2
	s_waitcnt lgkmcnt(1)
	v_pk_add_f32 v[14:15], v[14:15], v[16:17]
	ds_bpermute_b32 v5, v43, v3
	ds_bpermute_b32 v8, v43, v6
	ds_bpermute_b32 v9, v43, v7
	ds_bpermute_b32 v12, v43, v10
	ds_bpermute_b32 v13, v43, v11
	ds_bpermute_b32 v16, v43, v14
	ds_bpermute_b32 v17, v43, v15
	s_waitcnt lgkmcnt(6)
	v_pk_add_f32 v[2:3], v[2:3], v[4:5]
	s_waitcnt lgkmcnt(4)
	v_pk_add_f32 v[6:7], v[6:7], v[8:9]
	s_waitcnt lgkmcnt(2)
	v_pk_add_f32 v[10:11], v[10:11], v[12:13]
	ds_bpermute_b32 v4, v44, v2
	s_waitcnt lgkmcnt(1)
	v_pk_add_f32 v[14:15], v[14:15], v[16:17]
	ds_bpermute_b32 v5, v44, v3
	ds_bpermute_b32 v8, v44, v6
	ds_bpermute_b32 v9, v44, v7
	ds_bpermute_b32 v12, v44, v10
	ds_bpermute_b32 v13, v44, v11
	ds_bpermute_b32 v16, v44, v14
	ds_bpermute_b32 v17, v44, v15
	s_and_b64 exec, exec, s[6:7]
	s_cbranch_execz .LBB0_317
	v_and_b32_e32 v18, 0x3fffffc0, v156
	v_lshlrev_b32_e32 v18, 2, v18
	v_readlane_b32 s4, v254, 7
	s_waitcnt lgkmcnt(6)
	v_pk_add_f32 v[2:3], v[2:3], v[4:5]
	s_waitcnt lgkmcnt(4)
	v_pk_add_f32 v[4:5], v[6:7], v[8:9]
	v_add3_u32 v18, s4, v18, v158
	ds_write_b128 v18, v[2:5]
	s_waitcnt lgkmcnt(3)
	v_pk_add_f32 v[2:3], v[10:11], v[12:13]
	s_waitcnt lgkmcnt(1)
	v_pk_add_f32 v[4:5], v[14:15], v[16:17]
	ds_write_b128 v18, v[2:5] offset:16

; __device__ __forceinline__ float softplus_f(float x) { return fmaxf(x, 0.f) + log1pf(__expf(-fabsf(x))); }
; __device__ void prep_unit(unsigned char* lds, int bh, int n, const bf16_t* pc, const float* scal, const float* convw  , float alog, float dtb, unsigned char* unit, float* egl, unsigned* flag, unsigned fval) {
;     ...
;         const int t = tid - 384; const float* sp = scal + (row0 + t) * 16;
;         bet[t] = 1.0f / (1.0f + __expf(-sp[4 + h]));
;         gc[t] = -__expf(alog) * softplus_f(sp[8 + h] + dtb);
.Lps1_a:
	global_load_dword v224, v[8:9], off offset:16
	global_load_dword v225, v[8:9], off offset:32
	s_waitcnt vmcnt(0) lgkmcnt(0)
	s_branch .Lps1_back
